# attention half-workgroup stagger 18 instead of 12
# speedup vs baseline: 1.0009x; 1.0009x over previous
; #define LAS __attribute__((address_space(3)))
; #define PREFETCH(t) do { \
;         _Pragma("unroll") for (int i_ = 0; i_ < 4; ++i_) { const int pid_ = tid + 512 * i_, row_ = pid_ >> 4, c16_ = pid_ & 15; const unsigned go_ = (tokb + (unsigned)((t) * 128 + row_)) * 2048u + (unsigned)(hd * 128 + 8 * c16_); \
;             preK[i_] = *(const u32x4*)(Kb + go_); preV[i_] = *(const u32x4*)(Vb + go_); } \
;     } while (0)
; __device__ __forceinline__ void attn_unit(const PT& p, LAS unsigned char* lds, int tid, int lane, int wave, int b, int hd, int qb, float lam) {
;     ...
;         const int stg = t & 1;
;         if (t + 1 < ntiles) PREFETCH(t + 1);
;         const LAS unsigned char* kbase = kbase0 + stg * A_STAGE; const LAS unsigned char* vbase = vbase0 + stg * A_STAGE;
;         const bool diag = (t == qb);
; #pragma unroll 2
;         for (int sub = 0; sub < 2; ++sub) {
;             const int nact = diag ? min(2, max(0, wq + 1 - 2 * sub)) : 2;
;             if (nact > 0) {
;                 float sl = slope2; asm volatile("" : "+v"(sl));
;                 const float bq = sl * (float)(t * 128 + sub * 64 + 4 * h - q);
;                 const LAS unsigned char* kb0 = kbase + sub * 64 * AK_PITCH; const LAS unsigned char* vb0 = vbase + sub * 64 * AV_PITCH;
.LBB0_1078:
	s_and_b32 s87, s39, 1
	s_mul_i32 s88, s87, 0x11000
	v_add_u32_e32 v56, s88, v211
	s_add_i32 s36, s88, 0x8800
	v_add_u32_e32 v254, s36, v212
	s_cmp_lg_u32 s96, s38
	s_cselect_b64 s[82:83], -1, 0
	s_cmp_eq_u32 s96, s38
	s_cselect_b64 s[80:81], -1, 0
	s_or_b64 s[84:85], s[48:49], s[82:83]
	s_and_b64 vcc, exec, s[58:59]
	s_cbranch_vccz .Lat_nostagger
	s_sleep 18
